# static s_setprio 1 moved from waves 4-7 to waves 0-3 (older half); otherwise identical to previous
# baseline (speedup 1.0000x reference)
; __global__ void __launch_bounds__(512) fwd_megakernel(Prm p) {
;   __shared__ __attribute__((aligned(16))) unsigned char smem_raw[SMEM_BYTES];
;   bf16_t* sm = (bf16_t*)smem_raw;
;   __shared__ uint4 xb_words;
_Z14fwd_megakernel3Prm:
	s_mov_b32 s79, s2
	v_and_b32_e32 v203, 0x3ff, v0
	s_nop 1
	v_readfirstlane_b32 s100, v203
	s_nop 3
	s_cmp_ge_u32 s100, 0x100
	s_cbranch_scc1 .Lmy_noprio
	s_setprio 1
